# k32 + section 7.3: attention output tile stored with 4 dwordx4 (v_permlane32_swap pairs) instead of 8 dwordx2
# baseline (speedup 1.0000x reference)
.LBB0_1492:
	v_lshlrev_b32_e32 v36, 2, v189
	v_ashrrev_i32_e32 v37, 31, v36
	v_lshl_add_u64 v[34:35], v[36:37], 2, v[34:35]
	v_cvt_pk_bf16_f32 v40, v4, v5
	v_cvt_pk_bf16_f32 v41, v8, v9
	v_cvt_pk_bf16_f32 v42, v12, v13
	v_cvt_pk_bf16_f32 v43, v18, v19
	v_cvt_pk_bf16_f32 v44, v20, v21
	v_cvt_pk_bf16_f32 v45, v24, v25
	v_cvt_pk_bf16_f32 v46, v28, v29
	v_cvt_pk_bf16_f32 v47, v32, v33
	v_cvt_pk_bf16_f32 v48, v2, v3
	v_cvt_pk_bf16_f32 v49, v6, v7
	v_cvt_pk_bf16_f32 v50, v10, v11
	v_cvt_pk_bf16_f32 v51, v14, v15
	v_cvt_pk_bf16_f32 v52, v16, v17
	v_cvt_pk_bf16_f32 v53, v22, v23
	v_cvt_pk_bf16_f32 v54, v26, v27
	v_cvt_pk_bf16_f32 v55, v30, v31
	s_nop 1
	v_permlane32_swap_b32 v40, v42
	v_permlane32_swap_b32 v41, v43
	v_permlane32_swap_b32 v44, v46
	v_permlane32_swap_b32 v45, v47
	v_permlane32_swap_b32 v48, v50
	v_permlane32_swap_b32 v49, v51
	v_permlane32_swap_b32 v52, v54
	v_permlane32_swap_b32 v53, v55
	s_mov_b64 s[0:1], 0
	global_store_dwordx4 v[34:35], v[40:43], off
	global_store_dwordx4 v[34:35], v[44:47], off offset:32
	global_store_dwordx4 v[34:35], v[48:51], off offset:64
	global_store_dwordx4 v[34:35], v[52:55], off offset:96
